# P1 and P4 GEMM phases: workgroups start skewed by ((blockIdx>>3)&3) x s_sleep 6 (desynchronise chip-wide MFMA/load segments)
# speedup vs baseline: 1.0010x; 1.0010x over previous
.LBB0_244:
	v_readlane_b32 s4, v254, 9
	s_cmp_lt_i32 s4, 2
	s_cselect_b64 s[2:3], -1, 0
	s_and_b64 s[14:15], s[2:3], s[0:1]
	s_andn2_b64 vcc, exec, s[14:15]
	v_readlane_b32 s5, v254, 10
	v_readlane_b32 s6, v254, 11
	v_readlane_b32 s7, v254, 12
	s_cbranch_vccnz .LBB0_428
	s_lshr_b32 s100, s88, 3
	s_and_b32 s100, s100, 3
.Lskew_p1:
	s_cmp_eq_u32 s100, 0
	s_cbranch_scc1 .Lskew_done_p1
	s_sleep 6
	s_sub_u32 s100, s100, 1
	s_branch .Lskew_p1
.Lskew_done_p1:
	s_cmpk_lt_i32 s88, 0x300
	s_cselect_b64 s[4:5], -1, 0
	s_cmpk_gt_i32 s88, 0x2ff
	v_readfirstlane_b32 s6, v226
	s_cbranch_scc1 .LBB0_247
	s_ashr_i32 s0, s88, 31
	s_lshr_b32 s0, s0, 29
	s_add_i32 s0, s88, s0
	s_ashr_i32 s1, s0, 3
	s_and_b32 s0, s0, -8
	s_sub_i32 s0, s88, s0
	s_cmp_lt_i32 s0, 0
	s_movk_i32 s2, 0x61
	s_cselect_b32 s2, s2, 0x60
	s_mul_i32 s0, s2, s0
	s_add_i32 s0, s0, s1
	s_mul_hi_i32 s1, s0, 0x2aaaaaab
	s_lshr_b32 s2, s1, 31
	s_ashr_i32 s1, s1, 4
	s_add_i32 s1, s1, s2
	s_lshl_b32 s2, s1, 3
	s_mulk_i32 s1, 0x60
	s_sub_i32 s0, s0, s1
	s_bfe_i32 s1, s0, 0x80000
	s_bfe_u32 s1, s1, 0x3000c
	s_add_i32 s1, s0, s1
	s_bfe_i32 s3, s1, 0x80000
	s_and_b32 s1, s1, 0xf8
	s_sub_i32 s0, s0, s1
	s_sext_i32_i16 s3, s3
	s_sext_i32_i8 s0, s0
	s_add_i32 s0, s2, s0
	s_ashr_i32 s2, s3, 3

.LBB0_756:
	s_cmp_lt_i32 s76, 5
	s_cselect_b64 s[2:3], -1, 0
	s_and_b64 s[14:15], s[2:3], s[0:1]
	s_andn2_b64 vcc, exec, s[14:15]
	s_cbranch_vccnz .LBB0_857
	s_lshr_b32 s100, s88, 3
	s_and_b32 s100, s100, 3

.Lskew_done_p4:
	s_cmpk_lt_i32 s88, 0x180
	s_cselect_b64 s[4:5], -1, 0
	s_cmpk_gt_i32 s88, 0x17f
	v_readfirstlane_b32 s6, v226
	s_cbranch_scc1 .LBB0_759
	s_ashr_i32 s0, s88, 31
	s_lshr_b32 s0, s0, 29
	s_add_i32 s0, s88, s0
	s_ashr_i32 s1, s0, 3
	s_and_b32 s0, s0, -8
	s_sub_i32 s0, s88, s0
	s_cmp_lt_i32 s0, 0
	s_cselect_b32 s2, 49, 48
	s_mul_i32 s0, s2, s0
	s_add_i32 s0, s0, s1
	s_mul_hi_i32 s1, s0, 0x2aaaaaab
	s_lshr_b32 s2, s1, 31
	s_ashr_i32 s1, s1, 3
	s_add_i32 s1, s1, s2
	s_lshl_b32 s2, s1, 3
	s_mul_i32 s1, s1, 48
	s_sub_i32 s0, s0, s1
	s_bfe_i32 s1, s0, 0x80000
	s_bfe_u32 s1, s1, 0x3000c
	s_add_i32 s1, s0, s1
	s_bfe_i32 s3, s1, 0x80000
	s_and_b32 s1, s1, 0xf8
	s_sub_i32 s0, s0, s1
	s_sext_i32_i16 s3, s3
	s_sext_i32_i8 s0, s0
	s_add_i32 s0, s2, s0
	s_ashr_i32 s2, s3, 3
